# all 12 GEMM phase prologues: second tile batch issued before the first wait+barrier (one memory round trip instead of two at phase start)
# baseline (speedup 1.0000x reference)
; #define PG8_STAGE(bufoff, gbase, voff) do { _Pragma("unroll") for (int _i = 0; _i < 2; ++_i) \
;         __builtin_amdgcn_global_load_lds((const unsigned*)((const char*)(gbase) + (voff)[_i]), (LAS unsigned*)(lds + (bufoff) + ldsw + _i * 8192), 16, 0, 0); } while (0)
; #define PG8_WAIT_V(n) asm volatile("s_waitcnt vmcnt(" #n ")" ::: "memory")
; #define PG8_BAR __builtin_amdgcn_s_barrier()
; template <class Epi, class Sched>
; __device__ __forceinline__ void gemm_phase(const int tid, LAS unsigned char* lds, const int lda, const int ldb, const int K, const Sched& S, const Epi& E) {
;     ...
;     PG8_STAGE(PG8_SB(0, 0), cB, voffB); PG8_STAGE(PG8_SB(0, 1), cB + hstepB, voffB); PG8_STAGE(PG8_SA(0, 0), cA, voffA); PG8_STAGE(PG8_SA(0, 1), cA + hstepA, voffA);
;     if (wr == 1) PG8_BAR;
;     PG8_WAIT_V(2); PG8_BAR;
;     PG8_STAGE(PG8_SB(1, 0), cB + kstep, voffB); PG8_STAGE(PG8_SA(1, 0), cA + kstep, voffA); PG8_STAGE(PG8_SB(1, 1), cB + hstepB + kstep, voffB);
;     PG8_WAIT_V(6); PG8_BAR;
.LBB0_42:
	s_add_i32 m0, s26, 0x18000
	v_lshl_add_u64 v[142:143], v[142:143], 0, s[6:7]
	s_lshl_b32 s4, s36, 13
	s_lshl_b32 s24, s29, 12
	global_load_lds_dwordx4 v[142:143], off
	v_lshl_add_u64 v[140:141], v[140:141], 0, s[6:7]
	s_add_i32 m0, s26, 0x1a000
	s_add_i32 s65, s26, 0x8000
	s_add_i32 s66, s26, 0xa000
	global_load_lds_dwordx4 v[140:141], off
	v_lshl_add_u64 v[136:137], v[136:137], 0, s[6:7]
	s_mov_b32 m0, s65
	s_add_u32 s36, s52, 0xb0080
	global_load_lds_dwordx4 v[136:137], off
	v_lshl_add_u64 v[136:137], v[138:139], 0, s[6:7]
	s_mov_b32 m0, s66
	s_addc_u32 s37, s53, 0
	global_load_lds_dwordx4 v[136:137], off
	s_add_i32 m0, s26, 0x1c000
	v_lshl_add_u64 v[136:137], s[36:37], 0, v[130:131]
	global_load_lds_dwordx4 v[136:137], off
	v_lshl_add_u64 v[136:137], s[36:37], 0, v[134:135]
	s_add_i32 m0, s26, 0x1e000
	s_movk_i32 s14, 0x3c0
	global_load_lds_dwordx4 v[136:137], off
	s_waitcnt vmcnt(8)
	s_barrier
	v_lshlrev_b32_e32 v136, 6, v146
	v_lshlrev_b32_e32 v137, 4, v158
	v_lshlrev_b32_e32 v138, 2, v146
	v_and_or_b32 v136, v136, s14, v137
	v_and_b32_e32 v138, 32, v138
	v_bitop3_b32 v143, v136, s4, v138 bitop3:0xde
	v_lshlrev_b32_e32 v138, 2, v150
	v_lshlrev_b32_e32 v139, 6, v158
	s_movk_i32 s4, 0x80
	v_bitop3_b32 v151, v139, s4, v138 bitop3:0x36
	s_movk_i32 s4, 0xb00
	v_lshl_or_b32 v136, v150, 6, v137
	v_and_b32_e32 v137, 32, v138
	v_bitop3_b32 v150, v139, 64, v138 bitop3:0x36
	v_lshrrev_b32_e32 v139, 1, v144
	v_mul_lo_u32 v138, v152, s4
	s_mov_b32 s14, 0xb000
	v_mad_u64_u32 v[138:139], s[46:47], v139, s14, v[138:139]
	v_lshrrev_b32_e32 v141, 1, v154
	v_mul_lo_u32 v140, v156, s4
	s_cmp_gt_i32 s21, 0
	v_or_b32_e32 v138, v138, v145
	v_mad_u64_u32 v[140:141], s[46:47], v141, s14, v[140:141]
	s_waitcnt vmcnt(6)
	s_cselect_b64 s[42:43], -1, 0
	s_add_i32 s68, s21, -2
	v_add_lshl_u32 v168, v138, v153, 1
	s_mov_b64 s[48:49], 0xb0080
	v_or_b32_e32 v140, v140, v155
	v_lshlrev_b32_e32 v142, 3, v158
	s_cmpk_lt_u32 s38, 0x100
	v_lshl_add_u64 v[138:139], v[168:169], 0, s[48:49]
	v_add_lshl_u32 v168, v140, v157, 1
	v_bitop3_b32 v137, s24, v136, v137 bitop3:0xf6
	s_mov_b32 s67, 0
	s_cselect_b64 s[44:45], -1, 0
	v_or_b32_e32 v136, s39, v142
	v_cmp_eq_u32_e64 s[36:37], 0, v158
	s_ashr_i32 s69, s30, 31
	s_ashr_i32 s70, s28, 31
	v_lshl_add_u64 v[140:141], v[168:169], 0, s[48:49]
	v_add_u32_e32 v152, 0, v143
	s_lshl_b32 s4, s39, 2
	v_lshlrev_b32_e32 v168, 2, v142
	s_barrier
	s_branch .LBB0_45

; #define PG8_STAGE(bufoff, gbase, voff) do { _Pragma("unroll") for (int _i = 0; _i < 2; ++_i) \
;         __builtin_amdgcn_global_load_lds((const unsigned*)((const char*)(gbase) + (voff)[_i]), (LAS unsigned*)(lds + (bufoff) + ldsw + _i * 8192), 16, 0, 0); } while (0)
; #define PG8_WAIT_V(n) asm volatile("s_waitcnt vmcnt(" #n ")" ::: "memory")
; #define PG8_BAR __builtin_amdgcn_s_barrier()
; template <class Epi, class Sched>
; __device__ __forceinline__ void gemm_phase(const int tid, LAS unsigned char* lds, const int lda, const int ldb, const int K, const Sched& S, const Epi& E) {
;     ...
;     PG8_STAGE(PG8_SB(0, 0), cB, voffB); PG8_STAGE(PG8_SB(0, 1), cB + hstepB, voffB); PG8_STAGE(PG8_SA(0, 0), cA, voffA); PG8_STAGE(PG8_SA(0, 1), cA + hstepA, voffA);
;     if (wr == 1) PG8_BAR;
;     PG8_WAIT_V(2); PG8_BAR;
;     PG8_STAGE(PG8_SB(1, 0), cB + kstep, voffB); PG8_STAGE(PG8_SA(1, 0), cA + kstep, voffA); PG8_STAGE(PG8_SB(1, 1), cB + hstepB + kstep, voffB);
;     PG8_WAIT_V(6); PG8_BAR;
.LBB0_111:
	s_add_i32 m0, s26, 0x18000
	v_lshl_add_u64 v[140:141], v[140:141], 0, s[6:7]
	s_lshl_b32 s4, s37, 13
	s_lshl_b32 s14, s60, 12
	global_load_lds_dwordx4 v[140:141], off
	v_lshl_add_u64 v[138:139], v[138:139], 0, s[6:7]
	s_add_i32 m0, s26, 0x1a000
	s_add_i32 s65, s26, 0x8000
	s_add_i32 s66, s26, 0xa000
	global_load_lds_dwordx4 v[138:139], off
	v_lshl_add_u64 v[136:137], v[136:137], 0, s[6:7]
	s_mov_b32 m0, s65
	s_add_u32 s40, s50, 0x40080
	global_load_lds_dwordx4 v[136:137], off
	v_lshl_add_u64 v[136:137], v[142:143], 0, s[6:7]
	s_mov_b32 m0, s66
	s_addc_u32 s41, s51, 0
	global_load_lds_dwordx4 v[136:137], off
	s_add_i32 m0, s26, 0x1c000
	v_lshl_add_u64 v[136:137], s[40:41], 0, v[130:131]
	global_load_lds_dwordx4 v[136:137], off
	v_lshl_add_u64 v[136:137], s[40:41], 0, v[134:135]
	s_add_i32 m0, s26, 0x1e000
	s_movk_i32 s15, 0x3c0
	global_load_lds_dwordx4 v[136:137], off
	s_waitcnt vmcnt(8)
	s_barrier
	v_lshlrev_b32_e32 v136, 6, v146
	v_lshlrev_b32_e32 v137, 4, v156
	v_lshlrev_b32_e32 v138, 2, v146
	v_and_or_b32 v136, v136, s15, v137
	v_and_b32_e32 v138, 32, v138
	v_bitop3_b32 v143, v136, s4, v138 bitop3:0xde
	v_lshlrev_b32_e32 v138, 2, v150
	v_lshlrev_b32_e32 v139, 6, v156
	s_movk_i32 s4, 0x80
	v_lshl_or_b32 v136, v150, 6, v137
	v_and_b32_e32 v137, 32, v138
	v_bitop3_b32 v150, v139, 64, v138 bitop3:0x36
	v_bitop3_b32 v151, v139, s4, v138 bitop3:0x36
	v_lshlrev_b32_e32 v138, 14, v144
	v_lshlrev_b32_e32 v140, 14, v153
	s_cmp_gt_i32 s59, 0
	v_and_b32_e32 v138, 0xffff8000, v138
	v_and_b32_e32 v140, 0xffff8000, v140
	s_waitcnt vmcnt(6)
	s_cselect_b64 s[40:41], -1, 0
	s_add_i32 s68, s59, -2
	v_lshl_add_u32 v138, v145, 11, v138
	v_and_b32_e32 v139, 1, v144
	v_lshl_add_u32 v140, v154, 11, v140
	v_and_b32_e32 v141, 1, v153
	v_lshlrev_b32_e32 v142, 3, v156
	s_cmpk_lt_u32 s36, 0x100
	v_lshl_or_b32 v138, v139, 6, v138
	v_lshl_or_b32 v140, v141, 6, v140
	v_bitop3_b32 v137, s14, v136, v137 bitop3:0xf6
	s_mov_b32 s67, 0
	s_cselect_b64 s[42:43], -1, 0
	v_or_b32_e32 v136, s38, v142
	v_cmp_eq_u32_e64 s[36:37], 0, v156
	s_ashr_i32 s69, s30, 31
	s_ashr_i32 s70, s28, 31
	v_lshl_add_u32 v138, v152, 1, v138
	v_mov_b32_e32 v139, v169
	v_lshl_add_u32 v140, v155, 1, v140
	v_mov_b32_e32 v141, v169
	v_add_u32_e32 v152, 0, v143
	s_lshl_b32 s4, s38, 2
	v_lshlrev_b32_e32 v168, 2, v142
	s_barrier
	s_branch .LBB0_114

; #define PG8_STAGE(bufoff, gbase, voff) do { _Pragma("unroll") for (int _i = 0; _i < 2; ++_i) \
;         __builtin_amdgcn_global_load_lds((const unsigned*)((const char*)(gbase) + (voff)[_i]), (LAS unsigned*)(lds + (bufoff) + ldsw + _i * 8192), 16, 0, 0); } while (0)
; #define PG8_WAIT_V(n) asm volatile("s_waitcnt vmcnt(" #n ")" ::: "memory")
; #define PG8_BAR __builtin_amdgcn_s_barrier()
; template <class Epi, class Sched>
; __device__ __forceinline__ void gemm_phase(const int tid, LAS unsigned char* lds, const int lda, const int ldb, const int K, const Sched& S, const Epi& E) {
;     ...
;     PG8_STAGE(PG8_SB(0, 0), cB, voffB); PG8_STAGE(PG8_SB(0, 1), cB + hstepB, voffB); PG8_STAGE(PG8_SA(0, 0), cA, voffA); PG8_STAGE(PG8_SA(0, 1), cA + hstepA, voffA);
;     if (wr == 1) PG8_BAR;
;     PG8_WAIT_V(2); PG8_BAR;
;     PG8_STAGE(PG8_SB(1, 0), cB + kstep, voffB); PG8_STAGE(PG8_SA(1, 0), cA + kstep, voffA); PG8_STAGE(PG8_SB(1, 1), cB + hstepB + kstep, voffB);
;     PG8_WAIT_V(6); PG8_BAR;
.LBB0_186:
	s_waitcnt vmcnt(0)
	v_mov_b32_e32 v80, v60
	v_mov_b32_e32 v81, v52
	v_mov_b32_e32 v52, v61
	v_mov_b32_e32 v60, v62
	v_mov_b32_e32 v61, v54
	v_mov_b32_e32 v54, v63
	v_pk_add_f32 v[52:53], v[80:81], v[52:53]
	v_pk_add_f32 v[54:55], v[60:61], v[54:55]
	s_lshl_b32 s15, s24, 5
	v_pk_add_f32 v[52:53], v[52:53], v[54:55]
	v_mov_b32_e32 v54, v56
	v_mov_b32_e32 v55, v44
	v_mov_b32_e32 v44, v57
	v_pk_add_f32 v[44:45], v[54:55], v[44:45]
	v_mov_b32_e32 v54, v58
	v_mov_b32_e32 v55, v46
	v_mov_b32_e32 v46, v59
	v_pk_add_f32 v[46:47], v[54:55], v[46:47]
	s_and_b32 s15, s15, 0x60
	v_pk_add_f32 v[44:45], v[44:45], v[46:47]
	v_mov_b32_e32 v46, v48
	v_mov_b32_e32 v47, v36
	v_mov_b32_e32 v36, v49
	v_pk_add_f32 v[36:37], v[46:47], v[36:37]
	v_mov_b32_e32 v46, v50
	v_mov_b32_e32 v47, v38
	v_mov_b32_e32 v38, v51
	v_pk_add_f32 v[38:39], v[46:47], v[38:39]
	s_add_i32 m0, s57, 0x18000
	v_pk_add_f32 v[36:37], v[36:37], v[38:39]
	v_mov_b32_e32 v38, v40
	v_mov_b32_e32 v39, v28
	v_mov_b32_e32 v28, v41
	v_pk_add_f32 v[28:29], v[38:39], v[28:29]
	v_mov_b32_e32 v38, v42
	v_mov_b32_e32 v39, v30
	v_mov_b32_e32 v30, v43
	v_pk_add_f32 v[30:31], v[38:39], v[30:31]
	s_lshl_b32 s14, s23, 13
	v_pk_add_f32 v[28:29], v[28:29], v[30:31]
	v_mov_b32_e32 v30, v32
	v_mov_b32_e32 v31, v20
	v_mov_b32_e32 v20, v33
	v_pk_add_f32 v[20:21], v[30:31], v[20:21]
	v_mov_b32_e32 v30, v34
	v_mov_b32_e32 v31, v22
	v_mov_b32_e32 v22, v35
	v_pk_add_f32 v[22:23], v[30:31], v[22:23]
	s_lshl_b32 s23, s15, 7
	v_pk_add_f32 v[20:21], v[20:21], v[22:23]
	v_mov_b32_e32 v22, v24
	v_mov_b32_e32 v23, v12
	v_mov_b32_e32 v12, v25
	v_lshl_add_u64 v[24:25], v[70:71], 0, s[6:7]
	global_load_lds_dwordx4 v[24:25], off
	v_lshl_add_u64 v[24:25], v[68:69], 0, s[6:7]
	s_add_i32 m0, s57, 0x1a000
	s_add_i32 s61, s57, 0x8000
	s_add_i32 s62, s57, 0xa000
	global_load_lds_dwordx4 v[24:25], off
	v_lshl_add_u64 v[24:25], v[64:65], 0, s[6:7]
	s_mov_b32 m0, s61
	s_add_u32 s36, s52, 0x40080
	global_load_lds_dwordx4 v[24:25], off
	v_lshl_add_u64 v[24:25], v[66:67], 0, s[6:7]
	s_mov_b32 m0, s62
	s_addc_u32 s37, s53, 0
	global_load_lds_dwordx4 v[24:25], off
	s_add_i32 m0, s57, 0x1c000
	v_lshl_add_u64 v[24:25], s[36:37], 0, v[130:131]
	global_load_lds_dwordx4 v[24:25], off
	v_lshl_add_u64 v[24:25], s[36:37], 0, v[134:135]
	s_add_i32 m0, s57, 0x1e000
	v_pk_add_f32 v[12:13], v[22:23], v[12:13]
	global_load_lds_dwordx4 v[24:25], off
	s_waitcnt vmcnt(8)
	s_barrier
	v_mov_b32_e32 v22, v26
	v_mov_b32_e32 v23, v14
	v_mov_b32_e32 v14, v27
	v_pk_add_f32 v[14:15], v[22:23], v[14:15]
	v_pk_add_f32 v[52:53], v[52:53], 0 op_sel_hi:[1,0]
	v_pk_add_f32 v[12:13], v[12:13], v[14:15]
	v_mov_b32_e32 v14, v16
	v_mov_b32_e32 v15, v4
	v_mov_b32_e32 v4, v17
	v_pk_add_f32 v[44:45], v[52:53], v[44:45]
	v_pk_add_f32 v[4:5], v[14:15], v[4:5]
	v_mov_b32_e32 v14, v18
	v_mov_b32_e32 v15, v6
	v_mov_b32_e32 v6, v19
	v_pk_add_f32 v[36:37], v[44:45], v[36:37]
	v_pk_add_f32 v[6:7], v[14:15], v[6:7]
	v_pk_add_f32 v[28:29], v[36:37], v[28:29]
	v_pk_add_f32 v[4:5], v[4:5], v[6:7]
	v_mov_b32_e32 v6, v8
	v_mov_b32_e32 v7, v0
	v_mov_b32_e32 v0, v9
	v_pk_add_f32 v[20:21], v[28:29], v[20:21]
	v_pk_add_f32 v[0:1], v[6:7], v[0:1]
	v_mov_b32_e32 v6, v10
	v_mov_b32_e32 v7, v2
	v_mov_b32_e32 v2, v11
	v_pk_add_f32 v[12:13], v[20:21], v[12:13]
	v_pk_add_f32 v[2:3], v[6:7], v[2:3]
	v_pk_add_f32 v[4:5], v[12:13], v[4:5]
	v_pk_add_f32 v[0:1], v[0:1], v[2:3]
	s_mov_b32 s24, 0x3a800000
	v_pk_add_f32 v[0:1], v[4:5], v[0:1]
	s_sext_i32_i8 s27, s2
	v_pk_fma_f32 v[0:1], v[0:1], s[24:25], v[170:171] op_sel_hi:[1,0,0]
	s_mov_b32 s2, 0x45800000
	v_mul_f32_e32 v2, 0x4b800000, v1
	v_cmp_gt_f32_e32 vcc, s33, v1
	v_cmp_gt_f32_e64 s[36:37], s33, v0
	v_or_b32_e32 v144, s3, v142
	v_cndmask_b32_e32 v1, v1, v2, vcc
	v_mul_f32_e32 v2, 0x4b800000, v0
	v_cndmask_b32_e64 v0, v0, v2, s[36:37]
	v_rsq_f32_e32 v1, v1
	v_rsq_f32_e32 v0, v0
	v_lshlrev_b32_e32 v145, 2, v142
	s_cmp_gt_i32 s4, 0
	s_waitcnt vmcnt(6)
	v_pk_mul_f32 v[2:3], v[0:1], s[2:3] op_sel_hi:[1,0]
	s_movk_i32 s2, 0x3c0
	v_cndmask_b32_e32 v141, v1, v3, vcc
	v_cndmask_b32_e64 v140, v0, v2, s[36:37]
	v_lshlrev_b32_e32 v0, 6, v144
	v_lshlrev_b32_e32 v1, 2, v144
	v_and_or_b32 v0, v0, s2, v79
	v_and_b32_e32 v1, 32, v1
	v_bitop3_b32 v0, v0, s14, v1 bitop3:0xde
	v_lshl_or_b32 v1, v142, 6, v79
	v_and_b32_e32 v2, 32, v145
	v_bitop3_b32 v146, s23, v1, v2 bitop3:0xf6
	v_lshlrev_b32_e32 v1, 14, v72
	v_and_b32_e32 v1, 0xffff8000, v1
	v_lshl_add_u32 v1, v73, 11, v1
	v_and_b32_e32 v2, 1, v72
	v_lshl_or_b32 v1, v2, 6, v1
	v_lshl_add_u32 v136, v74, 1, v1
	v_lshlrev_b32_e32 v1, 14, v75
	v_and_b32_e32 v1, 0xffff8000, v1
	s_cselect_b64 s[42:43], -1, 0
	s_add_i32 s64, s4, -2
	v_lshl_add_u32 v1, v76, 11, v1
	v_and_b32_e32 v2, 1, v75
	s_cmpk_lt_u32 s22, 0x100
	v_lshl_or_b32 v1, v2, 6, v1
	s_mov_b32 s63, 0
	s_cselect_b64 s[44:45], -1, 0
	v_or_b32_e32 v147, 16, v144
	v_or_b32_e32 v148, 64, v145
	v_or_b32_e32 v149, 32, v144
	v_or_b32_e32 v150, 0x80, v145
	v_or_b32_e32 v151, 48, v144
	v_or_b32_e32 v152, 0xc0, v145
	s_ashr_i32 s65, s30, 31
	v_lshl_or_b32 v153, v78, 3, s15
	v_mov_b32_e32 v137, v169
	v_lshl_add_u32 v138, v77, 1, v1
	v_mov_b32_e32 v139, v169
	v_add_u32_e32 v154, 0, v0
	s_barrier
	s_branch .LBB0_189

; #define PG8_STAGE(bufoff, gbase, voff) do { _Pragma("unroll") for (int _i = 0; _i < 2; ++_i) \
;         __builtin_amdgcn_global_load_lds((const unsigned*)((const char*)(gbase) + (voff)[_i]), (LAS unsigned*)(lds + (bufoff) + ldsw + _i * 8192), 16, 0, 0); } while (0)
; #define PG8_WAIT_V(n) asm volatile("s_waitcnt vmcnt(" #n ")" ::: "memory")
; #define PG8_BAR __builtin_amdgcn_s_barrier()
; template <class Epi, class Sched>
; __device__ __forceinline__ void gemm_phase(const int tid, LAS unsigned char* lds, const int lda, const int ldb, const int K, const Sched& S, const Epi& E) {
;     ...
;     PG8_STAGE(PG8_SB(0, 0), cB, voffB); PG8_STAGE(PG8_SB(0, 1), cB + hstepB, voffB); PG8_STAGE(PG8_SA(0, 0), cA, voffA); PG8_STAGE(PG8_SA(0, 1), cA + hstepA, voffA);
;     if (wr == 1) PG8_BAR;
;     PG8_WAIT_V(2); PG8_BAR;
;     PG8_STAGE(PG8_SB(1, 0), cB + kstep, voffB); PG8_STAGE(PG8_SA(1, 0), cA + kstep, voffA); PG8_STAGE(PG8_SB(1, 1), cB + hstepB + kstep, voffB);
;     PG8_WAIT_V(6); PG8_BAR;
;     __device__ __forceinline__ void pre(const Unit& u, int wr, int wc, int fr, int fq, float& es0, float& es1) const {
;         int frl = fr; asm volatile("" : "+v"(frl));
;         const int l = fq * 16 + frl; es0 = row_rstd(SS, u.pn * 256 + (l >> 5) * 128 + wc * 32 + (l & 31)); es1 = 0.f;
.LBB0_208:
	s_waitcnt vmcnt(0)
	v_add_f32_e32 v12, v12, v13
	v_add_f32_e32 v14, v14, v15
	v_mov_b32_e32 v13, v18
	v_mov_b32_e32 v15, v19
	s_add_i32 m0, s51, 0x18000
	v_lshl_add_u64 v[18:19], v[38:39], 0, s[6:7]
	s_lshl_b32 s14, s3, 13
	s_lshl_b32 s15, s61, 7
	global_load_lds_dwordx4 v[18:19], off
	v_lshl_add_u64 v[18:19], v[36:37], 0, s[6:7]
	s_add_i32 m0, s51, 0x1a000
	s_add_i32 s65, s51, 0x8000
	s_add_i32 s66, s51, 0xa000
	global_load_lds_dwordx4 v[18:19], off
	v_lshl_add_u64 v[18:19], v[32:33], 0, s[6:7]
	s_mov_b32 m0, s65
	s_add_u32 s22, s56, 0x40080
	global_load_lds_dwordx4 v[18:19], off
	v_lshl_add_u64 v[18:19], v[34:35], 0, s[6:7]
	s_mov_b32 m0, s66
	s_addc_u32 s23, s57, 0
	global_load_lds_dwordx4 v[18:19], off
	s_add_i32 m0, s51, 0x1c000
	v_lshl_add_u64 v[18:19], s[22:23], 0, v[132:133]
	global_load_lds_dwordx4 v[18:19], off
	v_lshl_add_u64 v[18:19], s[22:23], 0, v[128:129]
	s_add_i32 m0, s51, 0x1e000
	v_mov_b32_e32 v48, v28
	global_load_lds_dwordx4 v[18:19], off
	s_waitcnt vmcnt(8)
	s_barrier
	v_mov_b32_e32 v49, v24
	v_mov_b32_e32 v24, v29
	v_mov_b32_e32 v28, v30
	v_mov_b32_e32 v29, v26
	v_mov_b32_e32 v26, v31
	v_pk_add_f32 v[24:25], v[48:49], v[24:25]
	v_pk_add_f32 v[26:27], v[28:29], v[26:27]
	v_pk_add_f32 v[12:13], v[12:13], v[14:15]
	v_pk_add_f32 v[24:25], v[24:25], v[26:27]
	v_mov_b32_e32 v26, v21
	v_mov_b32_e32 v27, v22
	v_mov_b32_e32 v21, v23
	v_pk_add_f32 v[20:21], v[26:27], v[20:21]
	v_add_f32_e32 v24, 0, v24
	v_pk_add_f32 v[20:21], v[20:21], v[20:21] op_sel:[0,1] op_sel_hi:[1,0]
	v_add_f32_e32 v24, v24, v25
	v_mov_b32_e32 v25, v16
	v_mov_b32_e32 v21, v17
	v_pk_add_f32 v[16:17], v[24:25], v[20:21]
	v_mov_b32_e32 v14, v9
	v_mov_b32_e32 v15, v10
	v_mov_b32_e32 v9, v11
	v_pk_add_f32 v[12:13], v[16:17], v[12:13]
	v_pk_add_f32 v[8:9], v[14:15], v[8:9]
	v_pk_add_f32 v[12:13], v[12:13], v[12:13] op_sel:[0,1] op_sel_hi:[1,0]
	v_pk_add_f32 v[8:9], v[8:9], v[8:9] op_sel:[0,1] op_sel_hi:[1,0]
	v_add_f32_e32 v4, v4, v5
	v_add_f32_e32 v6, v6, v7
	v_mov_b32_e32 v13, v0
	v_mov_b32_e32 v9, v1
	v_mov_b32_e32 v5, v2
	v_mov_b32_e32 v7, v3
	v_pk_add_f32 v[0:1], v[12:13], v[8:9]
	v_pk_add_f32 v[2:3], v[4:5], v[6:7]
	s_cmp_gt_i32 s13, 0
	v_pk_add_f32 v[0:1], v[0:1], v[2:3]
	v_lshlrev_b32_e32 v2, 2, v148
	v_add_f32_e32 v0, v0, v1
	v_fmamk_f32 v0, v0, 0x3a800000, v170
	v_mul_f32_e32 v1, 0x4b800000, v0
	v_cmp_gt_f32_e32 vcc, s33, v0
	v_and_b32_e32 v2, 32, v2
	s_waitcnt vmcnt(6)
	s_cselect_b64 s[40:41], -1, 0
	v_cndmask_b32_e32 v0, v0, v1, vcc
	v_rsq_f32_e32 v0, v0
	s_add_i32 s68, s13, -2
	v_lshl_or_b32 v150, s3, 6, v148
	s_cmpk_lt_u32 s2, 0x100
	v_mul_f32_e32 v1, 0x45800000, v0
	v_cndmask_b32_e32 v167, v0, v1, vcc
	v_lshl_or_b32 v1, v148, 6, v149
	v_bitop3_b32 v3, v1, s14, v2 bitop3:0xde
	v_bitop3_b32 v151, s15, v1, v2 bitop3:0xf6
	v_lshlrev_b32_e32 v1, 14, v45
	v_and_b32_e32 v1, 0xffff8000, v1
	v_lshl_add_u32 v1, v44, 11, v1
	v_and_b32_e32 v2, 1, v45
	v_lshl_or_b32 v1, v2, 6, v1
	v_lshl_add_u32 v136, v46, 1, v1
	v_lshlrev_b32_e32 v1, 14, v40
	v_and_b32_e32 v1, 0xffff8000, v1
	v_lshl_add_u32 v1, v42, 11, v1
	v_and_b32_e32 v2, 1, v40
	v_lshlrev_b32_e32 v0, 3, v41
	v_lshlrev_b32_e32 v152, 5, v41
	v_lshl_or_b32 v1, v2, 6, v1
	s_mov_b32 s67, 0
	s_cselect_b64 s[42:43], -1, 0
	v_or_b32_e32 v153, 24, v152
	v_or_b32_e32 v154, 28, v152
	v_or_b32_e32 v155, 16, v150
	v_or_b32_e32 v156, 32, v150
	v_or_b32_e32 v157, 48, v150
	v_or_b32_e32 v158, 0x80, v152
	v_or_b32_e32 v159, 0x84, v152
	v_or_b32_e32 v160, 0x88, v152
	v_or_b32_e32 v161, 0x8c, v152
	v_or_b32_e32 v162, 0x90, v152
	v_or_b32_e32 v163, 0x94, v152
	v_or_b32_e32 v164, 0x98, v152
	v_or_b32_e32 v165, 0x9c, v152
	v_mov_b32_e32 v137, v169
	v_lshl_add_u32 v138, v43, 1, v1
	v_mov_b32_e32 v139, v169
	v_add_u32_e32 v166, 0, v3
	s_lshl_b32 s22, s61, 1
	v_lshlrev_b32_e32 v168, 1, v0
	s_barrier
	s_branch .LBB0_211

; #define PG8_STAGE(bufoff, gbase, voff) do { _Pragma("unroll") for (int _i = 0; _i < 2; ++_i) \
;         __builtin_amdgcn_global_load_lds((const unsigned*)((const char*)(gbase) + (voff)[_i]), (LAS unsigned*)(lds + (bufoff) + ldsw + _i * 8192), 16, 0, 0); } while (0)
; #define PG8_WAIT_V(n) asm volatile("s_waitcnt vmcnt(" #n ")" ::: "memory")
; #define PG8_BAR __builtin_amdgcn_s_barrier()
; template <class Epi, class Sched>
; __device__ __forceinline__ void gemm_phase(const int tid, LAS unsigned char* lds, const int lda, const int ldb, const int K, const Sched& S, const Epi& E) {
;     ...
;     PG8_STAGE(PG8_SB(0, 0), cB, voffB); PG8_STAGE(PG8_SB(0, 1), cB + hstepB, voffB); PG8_STAGE(PG8_SA(0, 0), cA, voffA); PG8_STAGE(PG8_SA(0, 1), cA + hstepA, voffA);
;     if (wr == 1) PG8_BAR;
;     PG8_WAIT_V(2); PG8_BAR;
;     PG8_STAGE(PG8_SB(1, 0), cB + kstep, voffB); PG8_STAGE(PG8_SA(1, 0), cA + kstep, voffA); PG8_STAGE(PG8_SB(1, 1), cB + hstepB + kstep, voffB);
;     PG8_WAIT_V(6); PG8_BAR;
.LBB0_300:
	v_lshrrev_b32_e32 v15, 1, v203
	v_and_b32_e32 v15, 24, v15
	v_and_b32_e32 v14, 15, v203
	v_lshlrev_b32_e32 v16, 1, v15
	v_lshl_or_b32 v162, s2, 6, v14
	v_lshl_or_b32 v14, v14, 6, v16
	v_lshlrev_b32_e32 v16, 2, v203
	s_lshl_b32 s2, s2, 13
	v_and_b32_e32 v16, 32, v16
	v_bitop3_b32 v17, v14, s2, v16 bitop3:0xde
	s_lshl_b32 s2, s3, 5
	s_and_b32 s14, s2, 0x60
	s_lshl_b32 s2, s14, 7
	s_add_u32 s54, s10, 0x16000000
	s_addc_u32 s55, s11, 0
	s_add_i32 m0, s72, 0x18000
	v_lshl_add_u64 v[4:5], v[4:5], 0, s[6:7]
	global_load_lds_dwordx4 v[4:5], off
	v_lshl_add_u64 v[2:3], v[2:3], 0, s[6:7]
	s_add_i32 m0, s72, 0x1a000
	s_add_i32 s20, s72, 0x8000
	s_add_i32 s13, s72, 0xa000
	v_bitop3_b32 v163, s2, v14, v16 bitop3:0xf6
	global_load_lds_dwordx4 v[2:3], off
	v_lshl_add_u64 v[0:1], v[0:1], 0, s[6:7]
	s_mov_b32 m0, s20
	s_add_u32 s2, s68, 0x10080
	global_load_lds_dwordx4 v[0:1], off
	v_lshl_add_u64 v[0:1], v[6:7], 0, s[6:7]
	s_mov_b32 m0, s13
	s_addc_u32 s3, s69, 0
	global_load_lds_dwordx4 v[0:1], off
	s_add_i32 m0, s72, 0x1c000
	v_lshl_add_u64 v[0:1], s[2:3], 0, v[168:169]
	global_load_lds_dwordx4 v[0:1], off
	v_lshl_add_u64 v[0:1], s[2:3], 0, v[144:145]
	s_add_i32 m0, s72, 0x1e000
	s_cmp_gt_i32 s29, 0
	global_load_lds_dwordx4 v[0:1], off
	s_waitcnt vmcnt(8)
	s_barrier
	v_lshlrev_b32_e32 v0, 14, v8
	v_and_b32_e32 v0, 0xffff8000, v0
	v_lshl_add_u32 v0, v9, 11, v0
	v_and_b32_e32 v1, 1, v8
	v_lshl_or_b32 v0, v1, 6, v0
	v_lshl_add_u32 v146, v10, 1, v0
	v_lshlrev_b32_e32 v0, 14, v11
	v_and_b32_e32 v0, 0xffff8000, v0
	s_waitcnt vmcnt(6)
	s_cselect_b64 s[56:57], -1, 0
	s_add_i32 s45, s29, -2
	v_lshl_add_u32 v0, v12, 11, v0
	v_and_b32_e32 v1, 1, v11
	s_cmpk_lt_u32 s22, 0x100
	v_lshl_or_b32 v0, v1, 6, v0
	s_mov_b32 s44, 0
	s_cselect_b64 s[58:59], -1, 0
	v_or_b32_e32 v164, 16, v162
	v_or_b32_e32 v165, 32, v162
	v_or_b32_e32 v166, 48, v162
	s_ashr_i32 s22, s30, 31
	s_ashr_i32 s23, s28, 31
	v_or_b32_e32 v167, s14, v15
	v_mov_b32_e32 v147, v169
	v_lshl_add_u32 v148, v13, 1, v0
	v_mov_b32_e32 v149, v169
	v_add_u32_e32 v180, 0, v17
	s_barrier
	s_branch .LBB0_303

; #define PG8_STAGE(bufoff, gbase, voff) do { _Pragma("unroll") for (int _i = 0; _i < 2; ++_i) \
;         __builtin_amdgcn_global_load_lds((const unsigned*)((const char*)(gbase) + (voff)[_i]), (LAS unsigned*)(lds + (bufoff) + ldsw + _i * 8192), 16, 0, 0); } while (0)
; #define PG8_WAIT_V(n) asm volatile("s_waitcnt vmcnt(" #n ")" ::: "memory")
; #define PG8_BAR __builtin_amdgcn_s_barrier()
; template <class Epi, class Sched>
; __device__ __forceinline__ void gemm_phase(const int tid, LAS unsigned char* lds, const int lda, const int ldb, const int K, const Sched& S, const Epi& E) {
;     ...
;     PG8_STAGE(PG8_SB(0, 0), cB, voffB); PG8_STAGE(PG8_SB(0, 1), cB + hstepB, voffB); PG8_STAGE(PG8_SA(0, 0), cA, voffA); PG8_STAGE(PG8_SA(0, 1), cA + hstepA, voffA);
;     if (wr == 1) PG8_BAR;
;     PG8_WAIT_V(2); PG8_BAR;
;     PG8_STAGE(PG8_SB(1, 0), cB + kstep, voffB); PG8_STAGE(PG8_SA(1, 0), cA + kstep, voffA); PG8_STAGE(PG8_SB(1, 1), cB + hstepB + kstep, voffB);
;     PG8_WAIT_V(6); PG8_BAR;
.LBB0_608:
	s_add_i32 m0, s26, 0x18000
	v_lshl_add_u64 v[142:143], v[142:143], 0, s[6:7]
	s_lshl_b32 s4, s22, 13
	s_lshl_b32 s14, s58, 12
	global_load_lds_dwordx4 v[142:143], off
	v_lshl_add_u64 v[140:141], v[140:141], 0, s[6:7]
	s_add_i32 m0, s26, 0x1a000
	s_add_i32 s63, s26, 0x8000
	s_add_i32 s64, s26, 0xa000
	global_load_lds_dwordx4 v[140:141], off
	v_lshl_add_u64 v[136:137], v[136:137], 0, s[6:7]
	s_mov_b32 m0, s63
	s_add_u32 s22, s50, 0x40080
	global_load_lds_dwordx4 v[136:137], off
	v_lshl_add_u64 v[136:137], v[138:139], 0, s[6:7]
	s_mov_b32 m0, s64
	s_addc_u32 s23, s51, 0
	global_load_lds_dwordx4 v[136:137], off
	s_add_i32 m0, s26, 0x1c000
	v_lshl_add_u64 v[136:137], s[22:23], 0, v[130:131]
	global_load_lds_dwordx4 v[136:137], off
	v_lshl_add_u64 v[136:137], s[22:23], 0, v[134:135]
	s_add_i32 m0, s26, 0x1e000
	s_movk_i32 s15, 0x3c0
	global_load_lds_dwordx4 v[136:137], off
	s_waitcnt vmcnt(8)
	s_barrier
	v_lshlrev_b32_e32 v136, 6, v146
	v_lshlrev_b32_e32 v137, 4, v156
	v_lshlrev_b32_e32 v138, 2, v146
	v_and_or_b32 v136, v136, s15, v137
	v_and_b32_e32 v138, 32, v138
	v_bitop3_b32 v143, v136, s4, v138 bitop3:0xde
	v_lshlrev_b32_e32 v138, 2, v150
	v_lshlrev_b32_e32 v139, 6, v156
	s_movk_i32 s4, 0x80
	v_lshl_or_b32 v136, v150, 6, v137
	v_and_b32_e32 v137, 32, v138
	v_bitop3_b32 v150, v139, 64, v138 bitop3:0x36
	v_bitop3_b32 v151, v139, s4, v138 bitop3:0x36
	v_lshlrev_b32_e32 v138, 14, v144
	v_lshlrev_b32_e32 v140, 14, v153
	s_cmp_gt_i32 s31, 0
	v_and_b32_e32 v138, 0xffff8000, v138
	v_and_b32_e32 v140, 0xffff8000, v140
	s_waitcnt vmcnt(6)
	s_cselect_b64 s[22:23], -1, 0
	s_add_i32 s66, s31, -2
	v_lshl_add_u32 v138, v145, 11, v138
	v_and_b32_e32 v139, 1, v144
	v_lshl_add_u32 v140, v154, 11, v140
	v_and_b32_e32 v141, 1, v153
	v_lshlrev_b32_e32 v142, 3, v156
	s_cmpk_lt_u32 s36, 0x100
	v_lshl_or_b32 v138, v139, 6, v138
	v_lshl_or_b32 v140, v141, 6, v140
	v_bitop3_b32 v137, s14, v136, v137 bitop3:0xf6
	s_mov_b32 s65, 0
	s_cselect_b64 s[40:41], -1, 0
	v_or_b32_e32 v136, s38, v142
	v_cmp_eq_u32_e64 s[36:37], 0, v156
	s_ashr_i32 s67, s30, 31
	s_ashr_i32 s68, s28, 31
	v_lshl_add_u32 v138, v152, 1, v138
	v_mov_b32_e32 v139, v169
	v_lshl_add_u32 v140, v155, 1, v140
	v_mov_b32_e32 v141, v169
	v_add_u32_e32 v152, 0, v143
	s_lshl_b32 s4, s38, 2
	v_lshlrev_b32_e32 v168, 2, v142
	s_barrier
	s_branch .LBB0_611

; #define PG8_STAGE(bufoff, gbase, voff) do { _Pragma("unroll") for (int _i = 0; _i < 2; ++_i) \
;         __builtin_amdgcn_global_load_lds((const unsigned*)((const char*)(gbase) + (voff)[_i]), (LAS unsigned*)(lds + (bufoff) + ldsw + _i * 8192), 16, 0, 0); } while (0)
; #define PG8_WAIT_V(n) asm volatile("s_waitcnt vmcnt(" #n ")" ::: "memory")
; #define PG8_BAR __builtin_amdgcn_s_barrier()
; template <class Epi, class Sched>
; __device__ __forceinline__ void gemm_phase(const int tid, LAS unsigned char* lds, const int lda, const int ldb, const int K, const Sched& S, const Epi& E) {
;     ...
;     PG8_STAGE(PG8_SB(0, 0), cB, voffB); PG8_STAGE(PG8_SB(0, 1), cB + hstepB, voffB); PG8_STAGE(PG8_SA(0, 0), cA, voffA); PG8_STAGE(PG8_SA(0, 1), cA + hstepA, voffA);
;     if (wr == 1) PG8_BAR;
;     PG8_WAIT_V(2); PG8_BAR;
;     PG8_STAGE(PG8_SB(1, 0), cB + kstep, voffB); PG8_STAGE(PG8_SA(1, 0), cA + kstep, voffA); PG8_STAGE(PG8_SB(1, 1), cB + hstepB + kstep, voffB);
;     PG8_WAIT_V(6); PG8_BAR;
.LBB0_670:
	s_waitcnt vmcnt(0)
	v_mov_b32_e32 v80, v60
	v_mov_b32_e32 v81, v52
	v_mov_b32_e32 v52, v61
	v_mov_b32_e32 v60, v62
	v_mov_b32_e32 v61, v54
	v_mov_b32_e32 v54, v63
	v_pk_add_f32 v[52:53], v[80:81], v[52:53]
	v_pk_add_f32 v[54:55], v[60:61], v[54:55]
	s_lshl_b32 s14, s24, 5
	v_pk_add_f32 v[52:53], v[52:53], v[54:55]
	v_mov_b32_e32 v54, v56
	v_mov_b32_e32 v55, v44
	v_mov_b32_e32 v44, v57
	v_pk_add_f32 v[44:45], v[54:55], v[44:45]
	v_mov_b32_e32 v54, v58
	v_mov_b32_e32 v55, v46
	v_mov_b32_e32 v46, v59
	v_pk_add_f32 v[46:47], v[54:55], v[46:47]
	s_and_b32 s14, s14, 0x60
	v_pk_add_f32 v[44:45], v[44:45], v[46:47]
	v_mov_b32_e32 v46, v48
	v_mov_b32_e32 v47, v36
	v_mov_b32_e32 v36, v49
	v_pk_add_f32 v[36:37], v[46:47], v[36:37]
	v_mov_b32_e32 v46, v50
	v_mov_b32_e32 v47, v38
	v_mov_b32_e32 v38, v51
	v_pk_add_f32 v[38:39], v[46:47], v[38:39]
	s_add_i32 m0, s56, 0x18000
	v_pk_add_f32 v[36:37], v[36:37], v[38:39]
	v_mov_b32_e32 v38, v40
	v_mov_b32_e32 v39, v28
	v_mov_b32_e32 v28, v41
	v_pk_add_f32 v[28:29], v[38:39], v[28:29]
	v_mov_b32_e32 v38, v42
	v_mov_b32_e32 v39, v30
	v_mov_b32_e32 v30, v43
	v_pk_add_f32 v[30:31], v[38:39], v[30:31]
	s_lshl_b32 s3, s3, 13
	v_pk_add_f32 v[28:29], v[28:29], v[30:31]
	v_mov_b32_e32 v30, v32
	v_mov_b32_e32 v31, v20
	v_mov_b32_e32 v20, v33
	v_pk_add_f32 v[20:21], v[30:31], v[20:21]
	v_mov_b32_e32 v30, v34
	v_mov_b32_e32 v31, v22
	v_mov_b32_e32 v22, v35
	v_pk_add_f32 v[22:23], v[30:31], v[22:23]
	s_lshl_b32 s15, s14, 7
	v_pk_add_f32 v[20:21], v[20:21], v[22:23]
	v_mov_b32_e32 v22, v24
	v_mov_b32_e32 v23, v16
	v_mov_b32_e32 v16, v25
	v_pk_add_f32 v[16:17], v[22:23], v[16:17]
	v_mov_b32_e32 v22, v26
	v_mov_b32_e32 v23, v18
	v_mov_b32_e32 v18, v27
	v_pk_add_f32 v[18:19], v[22:23], v[18:19]
	v_lshl_add_u64 v[22:23], v[70:71], 0, s[6:7]
	global_load_lds_dwordx4 v[22:23], off
	v_lshl_add_u64 v[22:23], v[68:69], 0, s[6:7]
	s_add_i32 m0, s56, 0x1a000
	s_add_i32 s60, s56, 0x8000
	s_add_i32 s61, s56, 0xa000
	global_load_lds_dwordx4 v[22:23], off
	v_lshl_add_u64 v[22:23], v[64:65], 0, s[6:7]
	s_mov_b32 m0, s60
	s_add_u32 s36, s52, 0x40080
	global_load_lds_dwordx4 v[22:23], off
	v_lshl_add_u64 v[22:23], v[66:67], 0, s[6:7]
	s_mov_b32 m0, s61
	s_addc_u32 s37, s53, 0
	global_load_lds_dwordx4 v[22:23], off
	s_add_i32 m0, s56, 0x1c000
	v_lshl_add_u64 v[22:23], s[36:37], 0, v[130:131]
	global_load_lds_dwordx4 v[22:23], off
	v_lshl_add_u64 v[22:23], s[36:37], 0, v[134:135]
	s_add_i32 m0, s56, 0x1e000
	v_pk_add_f32 v[52:53], v[52:53], 0 op_sel_hi:[1,0]
	global_load_lds_dwordx4 v[22:23], off
	s_waitcnt vmcnt(8)
	s_barrier
	v_pk_add_f32 v[44:45], v[52:53], v[44:45]
	v_pk_add_f32 v[16:17], v[16:17], v[18:19]
	v_mov_b32_e32 v18, v12
	v_mov_b32_e32 v19, v4
	v_mov_b32_e32 v4, v13
	v_mov_b32_e32 v12, v14
	v_mov_b32_e32 v13, v6
	v_mov_b32_e32 v6, v15
	v_pk_add_f32 v[36:37], v[44:45], v[36:37]
	v_pk_add_f32 v[4:5], v[18:19], v[4:5]
	v_pk_add_f32 v[6:7], v[12:13], v[6:7]
	v_pk_add_f32 v[28:29], v[36:37], v[28:29]
	v_pk_add_f32 v[4:5], v[4:5], v[6:7]
	v_mov_b32_e32 v6, v8
	v_mov_b32_e32 v7, v0
	v_mov_b32_e32 v0, v9
	v_pk_add_f32 v[20:21], v[28:29], v[20:21]
	v_pk_add_f32 v[0:1], v[6:7], v[0:1]
	v_mov_b32_e32 v6, v10
	v_mov_b32_e32 v7, v2
	v_mov_b32_e32 v2, v11
	v_pk_add_f32 v[16:17], v[20:21], v[16:17]
	v_pk_add_f32 v[2:3], v[6:7], v[2:3]
	v_pk_add_f32 v[4:5], v[16:17], v[4:5]
	v_pk_add_f32 v[0:1], v[0:1], v[2:3]
	s_mov_b32 s24, 0x3a800000
	v_pk_add_f32 v[0:1], v[4:5], v[0:1]
	v_or_b32_e32 v150, s2, v148
	v_pk_fma_f32 v[0:1], v[0:1], s[24:25], v[170:171] op_sel_hi:[1,0,0]
	s_mov_b32 s24, 0x45800000
	v_mul_f32_e32 v2, 0x4b800000, v1
	v_cmp_gt_f32_e32 vcc, s33, v1
	v_cmp_gt_f32_e64 s[36:37], s33, v0
	s_movk_i32 s2, 0x3c0
	v_cndmask_b32_e32 v1, v1, v2, vcc
	v_mul_f32_e32 v2, 0x4b800000, v0
	v_cndmask_b32_e64 v0, v0, v2, s[36:37]
	v_rsq_f32_e32 v1, v1
	v_rsq_f32_e32 v0, v0
	v_lshlrev_b32_e32 v151, 2, v148
	s_cmp_gt_i32 s29, 0
	s_waitcnt vmcnt(6)
	v_pk_mul_f32 v[2:3], v[0:1], s[24:25] op_sel_hi:[1,0]
	s_cselect_b64 s[40:41], -1, 0
	v_cndmask_b32_e32 v141, v1, v3, vcc
	v_cndmask_b32_e64 v140, v0, v2, s[36:37]
	v_lshlrev_b32_e32 v0, 6, v150
	v_lshlrev_b32_e32 v1, 2, v150
	v_and_or_b32 v0, v0, s2, v79
	v_and_b32_e32 v1, 32, v1
	v_bitop3_b32 v0, v0, s3, v1 bitop3:0xde
	v_lshl_or_b32 v1, v148, 6, v79
	v_and_b32_e32 v2, 32, v151
	v_bitop3_b32 v152, s15, v1, v2 bitop3:0xf6
	v_lshlrev_b32_e32 v1, 14, v72
	v_and_b32_e32 v1, 0xffff8000, v1
	v_lshl_add_u32 v1, v73, 11, v1
	v_and_b32_e32 v2, 1, v72
	v_lshl_or_b32 v1, v2, 6, v1
	v_lshl_add_u32 v136, v74, 1, v1
	v_lshlrev_b32_e32 v1, 14, v75
	v_and_b32_e32 v1, 0xffff8000, v1
	s_add_i32 s63, s29, -2
	v_lshl_add_u32 v1, v76, 11, v1
	v_and_b32_e32 v2, 1, v75
	s_cmpk_lt_u32 s26, 0x100
	v_lshl_or_b32 v1, v2, 6, v1
	s_mov_b32 s62, 0
	s_cselect_b64 s[42:43], -1, 0
	v_or_b32_e32 v153, 16, v150
	v_or_b32_e32 v154, 64, v151
	v_or_b32_e32 v155, 32, v150
	v_or_b32_e32 v156, 0x80, v151
	v_or_b32_e32 v157, 48, v150
	v_or_b32_e32 v158, 0xc0, v151
	s_ashr_i32 s64, s30, 31
	s_ashr_i32 s65, s28, 31
	v_lshl_or_b32 v159, v78, 3, s14
	v_mov_b32_e32 v137, v169
	v_lshl_add_u32 v138, v77, 1, v1
	v_mov_b32_e32 v139, v169
	v_add_u32_e32 v160, 0, v0
	s_barrier
	s_branch .LBB0_673

; #define PG8_STAGE(bufoff, gbase, voff) do { _Pragma("unroll") for (int _i = 0; _i < 2; ++_i) \
;         __builtin_amdgcn_global_load_lds((const unsigned*)((const char*)(gbase) + (voff)[_i]), (LAS unsigned*)(lds + (bufoff) + ldsw + _i * 8192), 16, 0, 0); } while (0)
; #define PG8_WAIT_V(n) asm volatile("s_waitcnt vmcnt(" #n ")" ::: "memory")
; #define PG8_BAR __builtin_amdgcn_s_barrier()
; template <class Epi, class Sched>
; __device__ __forceinline__ void gemm_phase(const int tid, LAS unsigned char* lds, const int lda, const int ldb, const int K, const Sched& S, const Epi& E) {
;     ...
;     PG8_STAGE(PG8_SB(0, 0), cB, voffB); PG8_STAGE(PG8_SB(0, 1), cB + hstepB, voffB); PG8_STAGE(PG8_SA(0, 0), cA, voffA); PG8_STAGE(PG8_SA(0, 1), cA + hstepA, voffA);
;     if (wr == 1) PG8_BAR;
;     PG8_WAIT_V(2); PG8_BAR;
;     PG8_STAGE(PG8_SB(1, 0), cB + kstep, voffB); PG8_STAGE(PG8_SA(1, 0), cA + kstep, voffA); PG8_STAGE(PG8_SB(1, 1), cB + hstepB + kstep, voffB);
;     PG8_WAIT_V(6); PG8_BAR;
.LBB0_743:
	v_bfe_u32 v15, v203, 4, 2
	v_and_b32_e32 v14, 15, v203
	v_lshlrev_b32_e32 v17, 4, v15
	v_lshl_or_b32 v159, s3, 6, v14
	v_lshl_or_b32 v17, v14, 6, v17
	v_lshlrev_b32_e32 v14, 2, v14
	s_and_b32 s71, s2, 3
	s_lshl_b32 s2, s3, 13
	v_and_b32_e32 v18, 32, v14
	s_add_i32 m0, s31, 0x18000
	v_lshl_add_u64 v[4:5], v[4:5], 0, s[6:7]
	v_bitop3_b32 v19, v17, s2, v18 bitop3:0xde
	s_lshl_b32 s2, s71, 12
	global_load_lds_dwordx4 v[4:5], off
	v_lshl_add_u64 v[2:3], v[2:3], 0, s[6:7]
	s_add_i32 m0, s31, 0x1a000
	s_add_i32 s72, s31, 0x8000
	s_add_i32 s73, s31, 0xa000
	v_bitop3_b32 v182, s2, v17, v18 bitop3:0xf6
	global_load_lds_dwordx4 v[2:3], off
	v_lshl_add_u64 v[0:1], v[0:1], 0, s[6:7]
	s_mov_b32 m0, s72
	s_add_u32 s2, s66, 0x40080
	global_load_lds_dwordx4 v[0:1], off
	v_lshl_add_u64 v[0:1], v[6:7], 0, s[6:7]
	s_mov_b32 m0, s73
	s_addc_u32 s3, s67, 0
	global_load_lds_dwordx4 v[0:1], off
	s_add_i32 m0, s31, 0x1c000
	v_lshl_add_u64 v[0:1], s[2:3], 0, v[168:169]
	global_load_lds_dwordx4 v[0:1], off
	v_lshl_add_u64 v[0:1], s[2:3], 0, v[156:157]
	s_add_i32 m0, s31, 0x1e000
	s_cmp_gt_i32 s21, 0
	global_load_lds_dwordx4 v[0:1], off
	s_waitcnt vmcnt(8)
	s_barrier
	s_cselect_b64 s[52:53], -1, 0
	s_add_i32 s75, s21, -2
	s_cmpk_lt_u32 s22, 0x100
	v_lshlrev_b32_e32 v0, 6, v15
	s_movk_i32 s2, 0x80
	s_cselect_b64 s[54:55], -1, 0
	v_bitop3_b32 v184, v0, s2, v14 bitop3:0x36
	s_ashr_i32 s42, s30, 31
	s_ashr_i32 s43, s28, 31
	s_lshl_b32 s2, s71, 7
	s_add_u32 s2, s34, s2
	v_bitop3_b32 v183, v0, 64, v14 bitop3:0x36
	s_addc_u32 s3, s35, 0
	v_lshlrev_b32_e32 v0, 5, v15
	v_mov_b32_e32 v1, v169
	v_lshl_add_u64 v[160:161], s[2:3], 0, v[0:1]
	v_lshlrev_b32_e32 v0, 14, v8
	v_and_b32_e32 v0, 0xffff8000, v0
	v_lshl_add_u32 v0, v9, 11, v0
	v_and_b32_e32 v1, 1, v8
	v_lshl_or_b32 v0, v1, 6, v0
	v_lshl_add_u32 v162, v10, 1, v0
	v_lshlrev_b32_e32 v0, 14, v11
	v_and_b32_e32 v0, 0xffff8000, v0
	s_waitcnt vmcnt(6)
	v_lshl_add_u32 v0, v12, 11, v0
	v_and_b32_e32 v1, 1, v11
	v_lshlrev_b32_e32 v16, 3, v15
	v_lshl_or_b32 v0, v1, 6, v0
	s_mov_b32 s74, 0
	v_lshl_or_b32 v158, s71, 5, v16
	v_cmp_eq_u32_e64 s[36:37], 0, v15
	v_or_b32_e32 v185, 16, v159
	v_or_b32_e32 v186, 32, v159
	v_or_b32_e32 v187, 48, v159
	v_mov_b32_e32 v163, v169
	v_lshl_add_u32 v164, v13, 1, v0
	v_mov_b32_e32 v165, v169
	v_add_u32_e32 v188, 0, v19
	s_barrier
	s_branch .LBB0_746

; #define PG8_STAGE(bufoff, gbase, voff) do { _Pragma("unroll") for (int _i = 0; _i < 2; ++_i) \
;         __builtin_amdgcn_global_load_lds((const unsigned*)((const char*)(gbase) + (voff)[_i]), (LAS unsigned*)(lds + (bufoff) + ldsw + _i * 8192), 16, 0, 0); } while (0)
; #define PG8_WAIT_V(n) asm volatile("s_waitcnt vmcnt(" #n ")" ::: "memory")
; #define PG8_BAR __builtin_amdgcn_s_barrier()
; template <class Epi, class Sched>
; __device__ __forceinline__ void gemm_phase(const int tid, LAS unsigned char* lds, const int lda, const int ldb, const int K, const Sched& S, const Epi& E) {
;     ...
;     PG8_STAGE(PG8_SB(0, 0), cB, voffB); PG8_STAGE(PG8_SB(0, 1), cB + hstepB, voffB); PG8_STAGE(PG8_SA(0, 0), cA, voffA); PG8_STAGE(PG8_SA(0, 1), cA + hstepA, voffA);
;     if (wr == 1) PG8_BAR;
;     PG8_WAIT_V(2); PG8_BAR;
;     PG8_STAGE(PG8_SB(1, 0), cB + kstep, voffB); PG8_STAGE(PG8_SA(1, 0), cA + kstep, voffA); PG8_STAGE(PG8_SB(1, 1), cB + hstepB + kstep, voffB);
;     PG8_WAIT_V(6); PG8_BAR;
;     __device__ __forceinline__ void operator()(EPI_ARGS) const {
; #pragma unroll
;         for (int bj = 0; bj < 2; ++bj) {
;             const int nidx = u.pn * 256 + bj * 128 + wc * 32 + 8 * fq, tp = nidx >> 4, h0 = nidx & 15;
;             float dk[8];
; #pragma unroll
;             for (int e = 0; e < 8; ++e) dk[e] = dsk[u.g * 16 + h0 + e];
.LBB0_786:
	s_lshl_b32 s38, s18, 10
	v_lshrrev_b32_e32 v17, 1, v203
	s_ashr_i32 s39, s38, 31
	v_and_b32_e32 v18, 24, v17
	s_lshl_b64 s[38:39], s[38:39], 2
	v_and_b32_e32 v16, 15, v203
	v_lshlrev_b32_e32 v19, 1, v18
	s_add_u32 s38, s2, s38
	v_lshl_or_b32 v205, s26, 6, v16
	v_lshl_or_b32 v16, v16, 6, v19
	v_lshlrev_b32_e32 v19, 2, v203
	s_addc_u32 s39, s3, s39
	s_lshl_b32 s2, s26, 13
	v_and_b32_e32 v19, 32, v19
	v_bitop3_b32 v20, v16, s2, v19 bitop3:0xde
	s_lshl_b32 s2, s27, 5
	s_and_b32 s14, s2, 0x60
	s_add_i32 m0, s23, 0x18000
	v_lshl_add_u64 v[6:7], v[6:7], 0, s[6:7]
	s_lshl_b32 s2, s14, 7
	global_load_lds_dwordx4 v[6:7], off
	v_lshl_add_u64 v[4:5], v[4:5], 0, s[6:7]
	s_add_i32 m0, s23, 0x1a000
	s_add_i32 s47, s23, 0x8000
	s_add_i32 s70, s23, 0xa000
	v_bitop3_b32 v206, s2, v16, v19 bitop3:0xf6
	global_load_lds_dwordx4 v[4:5], off
	v_lshl_add_u64 v[0:1], v[0:1], 0, s[6:7]
	s_mov_b32 m0, s47
	s_add_u32 s2, s64, 0x28080
	global_load_lds_dwordx4 v[0:1], off
	v_lshl_add_u64 v[0:1], v[2:3], 0, s[6:7]
	s_mov_b32 m0, s70
	s_addc_u32 s3, s65, 0
	global_load_lds_dwordx4 v[0:1], off
	s_add_i32 m0, s23, 0x1c000
	v_lshl_add_u64 v[0:1], s[2:3], 0, v[182:183]
	global_load_lds_dwordx4 v[0:1], off
	v_lshl_add_u64 v[0:1], s[2:3], 0, v[186:187]
	s_add_i32 m0, s23, 0x1e000
	v_and_b32_e32 v188, 8, v17
	global_load_lds_dwordx4 v[0:1], off
	s_waitcnt vmcnt(8)
	s_barrier
	v_readlane_b32 s2, v255, 10
	v_or_b32_e32 v210, s14, v18
	s_movk_i32 s14, 0x280
	v_lshlrev_b32_e32 v168, 1, v188
	v_readlane_b32 s3, v255, 11
	v_lshrrev_b32_e32 v1, 1, v8
	v_mul_lo_u32 v0, v10, s14
	s_movk_i32 s15, 0x2800
	v_lshl_add_u64 v[190:191], s[2:3], 0, v[168:169]
	v_mad_u64_u32 v[0:1], s[2:3], v1, s15, v[0:1]
	v_or_b32_e32 v0, v0, v9
	v_add_lshl_u32 v168, v0, v11, 1
	v_lshrrev_b32_e32 v1, 1, v12
	v_mul_lo_u32 v0, v14, s14
	s_cmp_gt_i32 s4, 0
	v_mad_u64_u32 v[0:1], s[2:3], v1, s15, v[0:1]
	s_waitcnt vmcnt(6)
	s_cselect_b64 s[50:51], -1, 0
	s_add_i32 s72, s4, -2
	s_mov_b64 s[26:27], 0x28080
	v_or_b32_e32 v0, v0, v13
	s_cmpk_lt_u32 s24, 0x100
	v_lshl_add_u64 v[192:193], v[168:169], 0, s[26:27]
	v_add_lshl_u32 v168, v0, v15, 1
	s_mov_b32 s71, 0
	s_cselect_b64 s[52:53], -1, 0
	v_or_b32_e32 v207, 16, v205
	v_or_b32_e32 v208, 32, v205
	v_or_b32_e32 v209, 48, v205
	v_lshl_add_u64 v[194:195], v[168:169], 0, s[26:27]
	v_add_u32_e32 v211, 0, v20
	s_barrier
	s_branch .LBB0_789

; #define PG8_STAGE(bufoff, gbase, voff) do { _Pragma("unroll") for (int _i = 0; _i < 2; ++_i) \
;         __builtin_amdgcn_global_load_lds((const unsigned*)((const char*)(gbase) + (voff)[_i]), (LAS unsigned*)(lds + (bufoff) + ldsw + _i * 8192), 16, 0, 0); } while (0)
; #define PG8_WAIT_V(n) asm volatile("s_waitcnt vmcnt(" #n ")" ::: "memory")
; #define PG8_BAR __builtin_amdgcn_s_barrier()
; template <class Epi, class Sched>
; __device__ __forceinline__ void gemm_phase(const int tid, LAS unsigned char* lds, const int lda, const int ldb, const int K, const Sched& S, const Epi& E) {
;     ...
;     PG8_STAGE(PG8_SB(0, 0), cB, voffB); PG8_STAGE(PG8_SB(0, 1), cB + hstepB, voffB); PG8_STAGE(PG8_SA(0, 0), cA, voffA); PG8_STAGE(PG8_SA(0, 1), cA + hstepA, voffA);
;     if (wr == 1) PG8_BAR;
;     PG8_WAIT_V(2); PG8_BAR;
;     PG8_STAGE(PG8_SB(1, 0), cB + kstep, voffB); PG8_STAGE(PG8_SA(1, 0), cA + kstep, voffA); PG8_STAGE(PG8_SB(1, 1), cB + hstepB + kstep, voffB);
;     PG8_WAIT_V(6); PG8_BAR;
.LBB0_809:
	v_lshrrev_b32_e32 v16, 1, v203
	v_and_b32_e32 v16, 24, v16
	v_lshlrev_b32_e32 v17, 1, v16
	v_lshl_or_b32 v17, v137, 6, v17
	s_lshl_b32 s14, s24, 13
	v_and_b32_e32 v18, 32, v136
	s_lshl_b32 s4, s4, 5
	v_bitop3_b32 v19, v17, s14, v18 bitop3:0xde
	s_and_b32 s14, s4, 0x60
	s_lshl_b32 s4, s14, 7
	s_add_u32 s54, s10, 0x12800000
	s_addc_u32 s55, s11, 0
	s_add_i32 m0, s26, 0x18000
	v_lshl_add_u64 v[6:7], v[6:7], 0, s[6:7]
	global_load_lds_dwordx4 v[6:7], off
	v_lshl_add_u64 v[4:5], v[4:5], 0, s[6:7]
	s_add_i32 m0, s26, 0x1a000
	s_add_i32 s72, s26, 0x8000
	s_add_i32 s73, s26, 0xa000
	global_load_lds_dwordx4 v[4:5], off
	v_lshl_add_u64 v[0:1], v[0:1], 0, s[6:7]
	s_mov_b32 m0, s72
	s_add_u32 s40, s66, 0x20080
	global_load_lds_dwordx4 v[0:1], off
	v_lshl_add_u64 v[0:1], v[2:3], 0, s[6:7]
	s_mov_b32 m0, s73
	s_addc_u32 s41, s67, 0
	s_add_i32 s74, s26, 0x1c000
	global_load_lds_dwordx4 v[0:1], off
	v_lshl_add_u64 v[0:1], s[40:41], 0, v[168:169]
	s_mov_b32 m0, s74
	s_add_i32 s75, s26, 0x1e000
	global_load_lds_dwordx4 v[0:1], off
	v_lshl_add_u64 v[0:1], s[40:41], 0, v[64:65]
	s_mov_b32 m0, s75
	s_cmp_gt_i32 s22, 0
	global_load_lds_dwordx4 v[0:1], off
	s_waitcnt vmcnt(8)
	s_barrier
	v_bitop3_b32 v77, s4, v17, v18 bitop3:0xf6
	s_cselect_b64 s[40:41], -1, 0
	s_add_i32 s4, s22, -2
	s_cmpk_lt_u32 s23, 0x100
	s_cselect_b64 s[50:51], -1, 0
	s_lshl_b32 s14, s14, 2
	s_add_u32 s52, s54, s14
	v_writelane_b32 v255, s54, 20
	s_addc_u32 s53, s55, 0
	v_lshlrev_b32_e32 v0, 2, v16
	v_mov_b32_e32 v1, v169
	s_movk_i32 s14, 0x280
	v_lshl_add_u64 v[70:71], s[52:53], 0, v[0:1]
	v_lshrrev_b32_e32 v1, 1, v13
	v_mul_lo_u32 v0, v12, s14
	s_movk_i32 s15, 0x2800
	v_mad_u64_u32 v[0:1], s[52:53], v1, s15, v[0:1]
	v_or_b32_e32 v0, v0, v14
	v_writelane_b32 v255, s55, 21
	v_add_lshl_u32 v0, v0, v15, 1
	v_mov_b32_e32 v1, v169
	s_mov_b64 s[54:55], 0x28080
	v_lshl_add_u64 v[72:73], v[0:1], 0, s[54:55]
	v_lshrrev_b32_e32 v1, 1, v8
	v_mul_lo_u32 v0, v9, s14
	v_mad_u64_u32 v[0:1], s[52:53], v1, s15, v[0:1]
	s_waitcnt vmcnt(6)
	v_or_b32_e32 v0, v0, v10
	v_add_lshl_u32 v0, v0, v11, 1
	v_mov_b32_e32 v1, v169
	v_lshl_or_b32 v76, s24, 6, v137
	s_mov_b32 s37, 0
	v_lshl_add_u64 v[74:75], v[0:1], 0, s[54:55]
	v_add_u32_e32 v78, 0, v19
	s_barrier
	s_branch .LBB0_812

; #define PG8_STAGE(bufoff, gbase, voff) do { _Pragma("unroll") for (int _i = 0; _i < 2; ++_i) \
;         __builtin_amdgcn_global_load_lds((const unsigned*)((const char*)(gbase) + (voff)[_i]), (LAS unsigned*)(lds + (bufoff) + ldsw + _i * 8192), 16, 0, 0); } while (0)
; #define PG8_WAIT_V(n) asm volatile("s_waitcnt vmcnt(" #n ")" ::: "memory")
; #define PG8_BAR __builtin_amdgcn_s_barrier()
; template <class Epi, class Sched>
; __device__ __forceinline__ void gemm_phase(const int tid, LAS unsigned char* lds, const int lda, const int ldb, const int K, const Sched& S, const Epi& E) {
;     ...
;     PG8_STAGE(PG8_SB(0, 0), cB, voffB); PG8_STAGE(PG8_SB(0, 1), cB + hstepB, voffB); PG8_STAGE(PG8_SA(0, 0), cA, voffA); PG8_STAGE(PG8_SA(0, 1), cA + hstepA, voffA);
;     if (wr == 1) PG8_BAR;
;     PG8_WAIT_V(2); PG8_BAR;
;     PG8_STAGE(PG8_SB(1, 0), cB + kstep, voffB); PG8_STAGE(PG8_SA(1, 0), cA + kstep, voffA); PG8_STAGE(PG8_SB(1, 1), cB + hstepB + kstep, voffB);
;     PG8_WAIT_V(6); PG8_BAR;
.LBB0_863:
	s_waitcnt vmcnt(0)
	v_mov_b32_e32 v80, v60
	v_mov_b32_e32 v81, v52
	v_mov_b32_e32 v52, v61
	v_mov_b32_e32 v60, v62
	v_mov_b32_e32 v61, v54
	v_mov_b32_e32 v54, v63
	v_pk_add_f32 v[52:53], v[80:81], v[52:53]
	v_pk_add_f32 v[54:55], v[60:61], v[54:55]
	s_lshl_b32 s15, s24, 5
	v_pk_add_f32 v[52:53], v[52:53], v[54:55]
	v_mov_b32_e32 v54, v56
	v_mov_b32_e32 v55, v44
	v_mov_b32_e32 v44, v57
	v_pk_add_f32 v[44:45], v[54:55], v[44:45]
	v_mov_b32_e32 v54, v58
	v_mov_b32_e32 v55, v46
	v_mov_b32_e32 v46, v59
	v_pk_add_f32 v[46:47], v[54:55], v[46:47]
	v_pk_add_f32 v[52:53], v[52:53], 0 op_sel_hi:[1,0]
	v_pk_add_f32 v[44:45], v[44:45], v[46:47]
	v_mov_b32_e32 v46, v48
	v_mov_b32_e32 v47, v36
	v_mov_b32_e32 v36, v49
	v_pk_add_f32 v[36:37], v[46:47], v[36:37]
	v_mov_b32_e32 v46, v50
	v_mov_b32_e32 v47, v38
	v_mov_b32_e32 v38, v51
	v_pk_add_f32 v[38:39], v[46:47], v[38:39]
	v_pk_add_f32 v[44:45], v[52:53], v[44:45]
	v_pk_add_f32 v[36:37], v[36:37], v[38:39]
	v_mov_b32_e32 v38, v40
	v_mov_b32_e32 v39, v28
	v_mov_b32_e32 v28, v41
	v_pk_add_f32 v[28:29], v[38:39], v[28:29]
	v_mov_b32_e32 v38, v42
	v_mov_b32_e32 v39, v30
	v_mov_b32_e32 v30, v43
	v_pk_add_f32 v[30:31], v[38:39], v[30:31]
	v_pk_add_f32 v[36:37], v[44:45], v[36:37]
	v_pk_add_f32 v[28:29], v[28:29], v[30:31]
	v_mov_b32_e32 v30, v32
	v_mov_b32_e32 v31, v20
	v_mov_b32_e32 v20, v33
	v_pk_add_f32 v[20:21], v[30:31], v[20:21]
	v_mov_b32_e32 v30, v34
	v_mov_b32_e32 v31, v22
	v_mov_b32_e32 v22, v35
	v_pk_add_f32 v[22:23], v[30:31], v[22:23]
	v_pk_add_f32 v[28:29], v[36:37], v[28:29]
	v_pk_add_f32 v[20:21], v[20:21], v[22:23]
	v_mov_b32_e32 v22, v24
	v_mov_b32_e32 v23, v16
	v_mov_b32_e32 v16, v25
	v_pk_add_f32 v[16:17], v[22:23], v[16:17]
	v_mov_b32_e32 v22, v26
	v_mov_b32_e32 v23, v18
	v_mov_b32_e32 v18, v27
	v_pk_add_f32 v[18:19], v[22:23], v[18:19]
	v_pk_add_f32 v[20:21], v[28:29], v[20:21]
	v_pk_add_f32 v[16:17], v[16:17], v[18:19]
	s_and_b32 s15, s15, 0x60
	v_pk_add_f32 v[16:17], v[20:21], v[16:17]
	s_add_i32 m0, s21, 0x18000
	v_lshl_add_u64 v[20:21], v[70:71], 0, s[6:7]
	s_lshl_b32 s14, s27, 13
	s_lshl_b32 s24, s15, 7
	global_load_lds_dwordx4 v[20:21], off
	v_lshl_add_u64 v[20:21], v[68:69], 0, s[6:7]
	s_add_i32 m0, s21, 0x1a000
	s_add_i32 s57, s21, 0x8000
	s_add_i32 s58, s21, 0xa000
	global_load_lds_dwordx4 v[20:21], off
	v_lshl_add_u64 v[20:21], v[64:65], 0, s[6:7]
	s_mov_b32 m0, s57
	s_add_u32 s36, s52, 0x40080
	global_load_lds_dwordx4 v[20:21], off
	v_lshl_add_u64 v[20:21], v[66:67], 0, s[6:7]
	s_mov_b32 m0, s58
	s_addc_u32 s37, s53, 0
	global_load_lds_dwordx4 v[20:21], off
	s_add_i32 m0, s21, 0x1c000
	v_lshl_add_u64 v[20:21], s[36:37], 0, v[130:131]
	global_load_lds_dwordx4 v[20:21], off
	v_lshl_add_u64 v[20:21], s[36:37], 0, v[134:135]
	s_add_i32 m0, s21, 0x1e000
	v_mov_b32_e32 v18, v12
	global_load_lds_dwordx4 v[20:21], off
	s_waitcnt vmcnt(8)
	s_barrier
	v_mov_b32_e32 v19, v4
	v_mov_b32_e32 v4, v13
	v_mov_b32_e32 v12, v14
	v_mov_b32_e32 v13, v6
	v_mov_b32_e32 v6, v15
	v_pk_add_f32 v[4:5], v[18:19], v[4:5]
	v_pk_add_f32 v[6:7], v[12:13], v[6:7]
	s_mov_b32 s36, 0x3a800000
	v_pk_add_f32 v[4:5], v[4:5], v[6:7]
	v_mov_b32_e32 v6, v8
	v_mov_b32_e32 v7, v0
	v_mov_b32_e32 v0, v9
	v_pk_add_f32 v[0:1], v[6:7], v[0:1]
	v_mov_b32_e32 v6, v10
	v_mov_b32_e32 v7, v2
	v_mov_b32_e32 v2, v11
	v_pk_add_f32 v[2:3], v[6:7], v[2:3]
	v_pk_add_f32 v[4:5], v[16:17], v[4:5]
	v_pk_add_f32 v[0:1], v[0:1], v[2:3]
	s_sext_i32_i8 s27, s2
	v_pk_add_f32 v[0:1], v[4:5], v[0:1]
	s_mov_b32 s2, 0x45800000
	v_pk_fma_f32 v[0:1], v[0:1], s[36:37], v[170:171] op_sel_hi:[1,0,0]
	v_or_b32_e32 v146, s3, v144
	v_mul_f32_e32 v2, 0x4b800000, v1
	v_cmp_gt_f32_e32 vcc, s33, v1
	v_cmp_gt_f32_e64 s[36:37], s33, v0
	v_lshlrev_b32_e32 v147, 2, v144
	v_cndmask_b32_e32 v1, v1, v2, vcc
	v_mul_f32_e32 v2, 0x4b800000, v0
	v_cndmask_b32_e64 v0, v0, v2, s[36:37]
	v_rsq_f32_e32 v1, v1
	v_rsq_f32_e32 v0, v0
	v_and_b32_e32 v4, 1, v72
	s_cmp_gt_i32 s4, 0
	s_waitcnt vmcnt(6)
	v_pk_mul_f32 v[2:3], v[0:1], s[2:3] op_sel_hi:[1,0]
	s_movk_i32 s2, 0x3c0
	v_cndmask_b32_e64 v142, v0, v2, s[36:37]
	v_lshlrev_b32_e32 v0, 6, v146
	v_lshlrev_b32_e32 v2, 2, v146
	v_and_or_b32 v0, v0, s2, v78
	v_and_b32_e32 v2, 32, v2
	v_cndmask_b32_e32 v143, v1, v3, vcc
	v_bitop3_b32 v2, v0, s14, v2 bitop3:0xde
	v_lshl_or_b32 v0, v144, 6, v78
	v_and_b32_e32 v3, 32, v147
	v_bitop3_b32 v148, s24, v0, v3 bitop3:0xf6
	v_lshlrev_b32_e32 v3, 14, v72
	v_and_b32_e32 v3, 0xffff8000, v3
	v_lshl_add_u32 v3, v73, 11, v3
	v_lshl_or_b32 v3, v4, 6, v3
	v_lshl_add_u32 v136, v74, 1, v3
	v_lshlrev_b32_e32 v3, 14, v75
	v_and_b32_e32 v3, 0xffff8000, v3
	v_lshlrev_b32_e32 v1, 3, v79
	s_cselect_b64 s[40:41], -1, 0
	s_add_i32 s60, s4, -2
	v_lshl_add_u32 v3, v76, 11, v3
	v_and_b32_e32 v4, 1, v75
	s_cmpk_lt_u32 s38, 0x100
	v_and_b32_e32 v0, 8, v1
	v_or_b32_e32 v1, s15, v1
	v_lshl_or_b32 v3, v4, 6, v3
	s_mov_b32 s59, 0
	s_cselect_b64 s[42:43], -1, 0
	v_or_b32_e32 v149, 16, v146
	v_or_b32_e32 v150, 64, v147
	v_or_b32_e32 v151, 32, v146
	v_or_b32_e32 v152, 0x80, v147
	v_or_b32_e32 v153, 48, v146
	v_or_b32_e32 v154, 0xc0, v147
	s_ashr_i32 s61, s30, 31
	v_mov_b32_e32 v137, v169
	v_lshl_add_u32 v138, v77, 1, v3
	v_mov_b32_e32 v139, v169
	v_add_u32_e32 v155, 0, v2
	v_lshlrev_b32_e32 v156, 5, v1
	v_lshlrev_b32_e32 v140, 1, v0
	s_barrier
	s_branch .LBB0_866

; #define PG8_STAGE(bufoff, gbase, voff) do { _Pragma("unroll") for (int _i = 0; _i < 2; ++_i) \
;         __builtin_amdgcn_global_load_lds((const unsigned*)((const char*)(gbase) + (voff)[_i]), (LAS unsigned*)(lds + (bufoff) + ldsw + _i * 8192), 16, 0, 0); } while (0)
; #define PG8_WAIT_V(n) asm volatile("s_waitcnt vmcnt(" #n ")" ::: "memory")
; #define PG8_BAR __builtin_amdgcn_s_barrier()
; template <class Epi, class Sched>
; __device__ __forceinline__ void gemm_phase(const int tid, LAS unsigned char* lds, const int lda, const int ldb, const int K, const Sched& S, const Epi& E) {
;     ...
;     PG8_STAGE(PG8_SB(0, 0), cB, voffB); PG8_STAGE(PG8_SB(0, 1), cB + hstepB, voffB); PG8_STAGE(PG8_SA(0, 0), cA, voffA); PG8_STAGE(PG8_SA(0, 1), cA + hstepA, voffA);
;     if (wr == 1) PG8_BAR;
;     PG8_WAIT_V(2); PG8_BAR;
;     PG8_STAGE(PG8_SB(1, 0), cB + kstep, voffB); PG8_STAGE(PG8_SA(1, 0), cA + kstep, voffA); PG8_STAGE(PG8_SB(1, 1), cB + hstepB + kstep, voffB);
;     PG8_WAIT_V(6); PG8_BAR;
.LBB0_889:
	s_waitcnt vmcnt(0)
	v_mov_b32_e32 v80, v60
	v_mov_b32_e32 v81, v52
	v_mov_b32_e32 v52, v61
	v_mov_b32_e32 v60, v62
	v_mov_b32_e32 v61, v54
	v_mov_b32_e32 v54, v63
	v_pk_add_f32 v[52:53], v[80:81], v[52:53]
	v_pk_add_f32 v[54:55], v[60:61], v[54:55]
	s_lshl_b32 s27, s27, 5
	v_pk_add_f32 v[52:53], v[52:53], v[54:55]
	v_mov_b32_e32 v54, v56
	v_mov_b32_e32 v55, v44
	v_mov_b32_e32 v44, v57
	v_pk_add_f32 v[44:45], v[54:55], v[44:45]
	v_mov_b32_e32 v54, v58
	v_mov_b32_e32 v55, v46
	v_mov_b32_e32 v46, v59
	v_pk_add_f32 v[46:47], v[54:55], v[46:47]
	s_and_b32 s38, s27, 0x60
	v_pk_add_f32 v[44:45], v[44:45], v[46:47]
	v_mov_b32_e32 v46, v48
	v_mov_b32_e32 v47, v36
	v_mov_b32_e32 v36, v49
	v_pk_add_f32 v[36:37], v[46:47], v[36:37]
	v_mov_b32_e32 v46, v50
	v_mov_b32_e32 v47, v38
	v_mov_b32_e32 v38, v51
	v_pk_add_f32 v[38:39], v[46:47], v[38:39]
	s_add_i32 m0, s29, 0x18000
	v_pk_add_f32 v[36:37], v[36:37], v[38:39]
	v_mov_b32_e32 v38, v40
	v_mov_b32_e32 v39, v28
	v_mov_b32_e32 v28, v41
	v_pk_add_f32 v[28:29], v[38:39], v[28:29]
	v_mov_b32_e32 v38, v42
	v_mov_b32_e32 v39, v30
	v_mov_b32_e32 v30, v43
	v_pk_add_f32 v[30:31], v[38:39], v[30:31]
	s_lshl_b32 s24, s36, 13
	v_pk_add_f32 v[28:29], v[28:29], v[30:31]
	v_mov_b32_e32 v30, v32
	v_mov_b32_e32 v31, v20
	v_mov_b32_e32 v20, v33
	v_pk_add_f32 v[20:21], v[30:31], v[20:21]
	v_mov_b32_e32 v30, v34
	v_mov_b32_e32 v31, v22
	v_mov_b32_e32 v22, v35
	v_pk_add_f32 v[22:23], v[30:31], v[22:23]
	s_lshl_b32 s39, s38, 7
	v_pk_add_f32 v[20:21], v[20:21], v[22:23]
	v_mov_b32_e32 v22, v24
	v_mov_b32_e32 v23, v16
	v_mov_b32_e32 v16, v25
	v_pk_add_f32 v[16:17], v[22:23], v[16:17]
	v_mov_b32_e32 v22, v26
	v_mov_b32_e32 v23, v18
	v_mov_b32_e32 v18, v27
	v_pk_add_f32 v[18:19], v[22:23], v[18:19]
	v_pk_add_f32 v[16:17], v[16:17], v[18:19]
	v_lshl_add_u64 v[18:19], v[70:71], 0, s[6:7]
	global_load_lds_dwordx4 v[18:19], off
	v_lshl_add_u64 v[18:19], v[68:69], 0, s[6:7]
	s_add_i32 m0, s29, 0x1a000
	s_add_i32 s58, s29, 0x8000
	s_add_i32 s59, s29, 0xa000
	global_load_lds_dwordx4 v[18:19], off
	v_lshl_add_u64 v[18:19], v[64:65], 0, s[6:7]
	s_mov_b32 m0, s58
	s_add_u32 s36, s52, 0x40080
	global_load_lds_dwordx4 v[18:19], off
	v_lshl_add_u64 v[18:19], v[66:67], 0, s[6:7]
	s_mov_b32 m0, s59
	s_addc_u32 s37, s53, 0
	global_load_lds_dwordx4 v[18:19], off
	s_add_i32 m0, s29, 0x1c000
	v_lshl_add_u64 v[18:19], s[36:37], 0, v[132:133]
	global_load_lds_dwordx4 v[18:19], off
	v_lshl_add_u64 v[18:19], s[36:37], 0, v[128:129]
	s_add_i32 m0, s29, 0x1e000
	v_pk_add_f32 v[52:53], v[52:53], 0 op_sel_hi:[1,0]
	global_load_lds_dwordx4 v[18:19], off
	s_waitcnt vmcnt(8)
	s_barrier
	v_pk_add_f32 v[44:45], v[52:53], v[44:45]
	v_mov_b32_e32 v18, v12
	v_mov_b32_e32 v19, v4
	v_mov_b32_e32 v4, v13
	v_mov_b32_e32 v12, v14
	v_mov_b32_e32 v13, v6
	v_mov_b32_e32 v6, v15
	v_pk_add_f32 v[36:37], v[44:45], v[36:37]
	v_pk_add_f32 v[4:5], v[18:19], v[4:5]
	v_pk_add_f32 v[6:7], v[12:13], v[6:7]
	v_pk_add_f32 v[28:29], v[36:37], v[28:29]
	v_pk_add_f32 v[4:5], v[4:5], v[6:7]
	v_mov_b32_e32 v6, v8
	v_mov_b32_e32 v7, v0
	v_mov_b32_e32 v0, v9
	v_pk_add_f32 v[20:21], v[28:29], v[20:21]
	v_pk_add_f32 v[0:1], v[6:7], v[0:1]
	v_mov_b32_e32 v6, v10
	v_mov_b32_e32 v7, v2
	v_mov_b32_e32 v2, v11
	v_pk_add_f32 v[16:17], v[20:21], v[16:17]
	v_pk_add_f32 v[2:3], v[6:7], v[2:3]
	v_pk_add_f32 v[4:5], v[16:17], v[4:5]
	v_pk_add_f32 v[0:1], v[0:1], v[2:3]
	s_mov_b32 s14, 0x3a800000
	v_pk_add_f32 v[0:1], v[4:5], v[0:1]
	s_sext_i32_i16 s27, s2
	v_pk_fma_f32 v[0:1], v[0:1], s[14:15], v[170:171] op_sel_hi:[1,0,0]
	s_mov_b32 s2, 0x45800000
	v_mul_f32_e32 v2, 0x4b800000, v1
	v_cmp_gt_f32_e32 vcc, s33, v1
	v_cmp_gt_f32_e64 s[36:37], s33, v0
	v_or_b32_e32 v144, s4, v142
	v_cndmask_b32_e32 v1, v1, v2, vcc
	v_mul_f32_e32 v2, 0x4b800000, v0
	v_cndmask_b32_e64 v0, v0, v2, s[36:37]
	v_rsq_f32_e32 v1, v1
	v_rsq_f32_e32 v0, v0
	v_lshlrev_b32_e32 v145, 2, v142
	s_cmp_gt_i32 s13, 0
	s_waitcnt vmcnt(0)
	v_pk_mul_f32 v[2:3], v[0:1], s[2:3] op_sel_hi:[1,0]
	s_movk_i32 s2, 0x3c0
	v_cndmask_b32_e32 v141, v1, v3, vcc
	v_cndmask_b32_e64 v140, v0, v2, s[36:37]
	v_lshlrev_b32_e32 v1, 6, v144
	v_lshlrev_b32_e32 v2, 2, v144
	v_and_or_b32 v1, v1, s2, v75
	v_and_b32_e32 v2, 32, v2
	v_bitop3_b32 v1, v1, s24, v2 bitop3:0xde
	v_lshl_or_b32 v2, v142, 6, v75
	v_and_b32_e32 v3, 32, v145
	v_bitop3_b32 v146, s39, v2, v3 bitop3:0xf6
	v_lshlrev_b32_e32 v2, 14, v78
	v_and_b32_e32 v2, 0xffff8000, v2
	v_lshl_add_u32 v2, v77, 11, v2
	v_and_b32_e32 v3, 1, v78
	v_lshl_or_b32 v2, v3, 6, v2
	v_lshl_add_u32 v136, v79, 1, v2
	v_lshlrev_b32_e32 v2, 14, v72
	v_and_b32_e32 v2, 0xffff8000, v2
	s_cselect_b64 s[40:41], -1, 0
	s_add_i32 s61, s13, -2
	v_lshl_add_u32 v2, v73, 11, v2
	v_and_b32_e32 v3, 1, v72
	v_lshlrev_b32_e32 v0, 3, v76
	s_cmpk_lt_u32 s3, 0x100
	v_lshl_or_b32 v2, v3, 6, v2
	s_mov_b32 s60, 0
	s_cselect_b64 s[42:43], -1, 0
	v_or_b32_e32 v147, 16, v144
	v_or_b32_e32 v148, 64, v145
	v_or_b32_e32 v149, 32, v144
	v_or_b32_e32 v150, 0x80, v145
	v_or_b32_e32 v151, 48, v144
	v_or_b32_e32 v152, 0xc0, v145
	s_ashr_i32 s62, s30, 31
	v_mov_b32_e32 v137, v169
	v_lshl_add_u32 v138, v74, 1, v2
	v_mov_b32_e32 v139, v169
	v_add_u32_e32 v153, 0, v1
	s_lshl_b32 s4, s38, 1
	v_lshlrev_b32_e32 v168, 1, v0
	s_barrier
	s_branch .LBB0_892
